# GLA chunk-state phase: the current unit's MFMA/store block moved between the next unit's loads and their first use (five load destinations renamed), so the load round trip overlaps it
# baseline (speedup 1.0000x reference)
.LBB0_421:
	s_or_b64 exec, exec, s[22:23]
	s_waitcnt vmcnt(3)
	v_and_b32_e32 v20, 0xffff, v4
	s_waitcnt vmcnt(1)
	v_and_b32_e32 v35, 0xffff, v12
	v_lshl_or_b32 v20, v8, 16, v20
	s_waitcnt vmcnt(0)
	v_lshl_or_b32 v35, v16, 16, v35
	v_add_u32_e32 v72, 0x2800, v62
	v_lshrrev_b32_e32 v21, 16, v4
	s_mov_b32 s22, 0xffff0000
	ds_write2_b32 v72, v20, v35 offset1:16
	v_lshrrev_b32_e32 v20, 16, v12
	v_and_or_b32 v21, v8, s22, v21
	v_and_or_b32 v20, v16, s22, v20
	v_and_b32_e32 v22, 0xffff, v5
	ds_write2_b32 v72, v21, v20 offset0:36 offset1:52
	v_and_b32_e32 v20, 0xffff, v13
	v_lshl_or_b32 v22, v9, 16, v22
	v_lshl_or_b32 v20, v17, 16, v20
	v_lshrrev_b32_e32 v23, 16, v5
	ds_write2_b32 v72, v22, v20 offset0:72 offset1:88
	v_lshrrev_b32_e32 v20, 16, v13
	v_and_or_b32 v23, v9, s22, v23
	v_and_or_b32 v20, v17, s22, v20
	v_and_b32_e32 v24, 0xffff, v6
	ds_write2_b32 v72, v23, v20 offset0:108 offset1:124
	v_and_b32_e32 v20, 0xffff, v14
	v_lshl_or_b32 v24, v10, 16, v24
	v_lshl_or_b32 v20, v18, 16, v20
	v_lshrrev_b32_e32 v25, 16, v6
	ds_write2_b32 v72, v24, v20 offset0:144 offset1:160
	v_lshrrev_b32_e32 v20, 16, v14
	v_and_or_b32 v25, v10, s22, v25
	v_and_or_b32 v20, v18, s22, v20
	v_and_b32_e32 v26, 0xffff, v7
	ds_write2_b32 v72, v25, v20 offset0:180 offset1:196
	v_and_b32_e32 v20, 0xffff, v15
	v_lshl_or_b32 v26, v11, 16, v26
	v_lshl_or_b32 v20, v19, 16, v20
	s_add_i32 s24, s24, s86
	v_lshrrev_b32_e32 v27, 16, v7
	ds_write2_b32 v72, v26, v20 offset0:216 offset1:232
	v_lshrrev_b32_e32 v20, 16, v15
	s_cmpk_gt_i32 s24, 0x3ff
	v_and_or_b32 v27, v11, s22, v27
	v_and_or_b32 v20, v19, s22, v20
	s_cselect_b64 s[22:23], -1, 0
	v_add_u32_e32 v21, 0x2a00, v62
	s_and_b64 vcc, exec, s[22:23]
	ds_write2_b32 v21, v27, v20 offset0:124 offset1:140
	s_waitcnt lgkmcnt(0)
	s_barrier
	s_cbranch_vccnz .LBB0_418
	v_readlane_b32 s25, v254, 43
	v_mov_b64_e32 v[12:13], s[18:19]
	v_mov_b32_e32 v7, v2
	v_add_u32_e32 v4, s25, v3
	v_bfe_u32 v35, v4, 7, 2
	v_and_b32_e32 v4, 0x1fc0, v64
	s_movk_i32 s25, 0xe000
	v_and_or_b32 v36, v65, s25, v4
	v_or_b32_e32 v4, v36, v54
	v_or_b32_e32 v20, 2, v4
	v_or_b32_e32 v16, 1, v4
	v_ashrrev_i32_e32 v21, 31, v20
	v_or_b32_e32 v24, 3, v4
	v_lshlrev_b32_e32 v6, 7, v35
	v_ashrrev_i32_e32 v5, 31, v4
	v_ashrrev_i32_e32 v17, 31, v16
	v_lshlrev_b64 v[22:23], 9, v[20:21]
	v_mad_i64_i32 v[20:21], s[26:27], v20, s62, v[12:13]
	v_ashrrev_i32_e32 v25, 31, v24
	v_lshl_add_u64 v[8:9], v[28:29], 0, v[6:7]
	v_lshlrev_b64 v[10:11], 9, v[4:5]
	v_mad_i64_i32 v[14:15], s[26:27], v4, s62, v[12:13]
	v_mov_b32_e32 v33, v2
	v_lshlrev_b64 v[18:19], 9, v[16:17]
	v_mad_i64_i32 v[16:17], s[26:27], v16, s62, v[12:13]
	v_lshl_add_u64 v[20:21], v[20:21], 0, v[6:7]
	v_lshlrev_b64 v[26:27], 9, v[24:25]
	v_mad_i64_i32 v[24:25], s[26:27], v24, s62, v[12:13]
	v_lshl_add_u64 v[10:11], v[8:9], 0, v[10:11]
	v_lshl_add_u64 v[14:15], v[14:15], 0, v[6:7]
	v_lshl_add_u64 v[16:17], v[16:17], 0, v[6:7]
	v_lshl_add_u64 v[20:21], v[20:21], 0, v[32:33]
	v_lshl_add_u64 v[26:27], v[8:9], 0, v[26:27]
	v_lshl_add_u64 v[24:25], v[24:25], 0, v[6:7]
	v_lshl_add_u64 v[14:15], v[14:15], 0, v[32:33]
	v_lshl_add_u64 v[18:19], v[8:9], 0, v[18:19]
	v_lshl_add_u64 v[16:17], v[16:17], 0, v[32:33]
	v_lshl_add_u64 v[22:23], v[8:9], 0, v[22:23]
	v_lshl_add_u64 v[24:25], v[24:25], 0, v[32:33]
	global_load_dword v37, v[10:11], off
	global_load_dword v55, v[14:15], off offset:512
	global_load_dword v39, v[18:19], off
	global_load_dword v56, v[16:17], off offset:512
	global_load_dword v41, v[22:23], off
	global_load_dword v57, v[20:21], off offset:512
	s_nop 0
	global_load_dword v43, v[26:27], off
	s_nop 0
	global_load_dword v58, v[24:25], off offset:512
	v_or_b32_e32 v20, 6, v4
	v_or_b32_e32 v10, 4, v4
	v_or_b32_e32 v16, 5, v4
	v_ashrrev_i32_e32 v21, 31, v20
	v_or_b32_e32 v4, 7, v4
	v_ashrrev_i32_e32 v11, 31, v10
	v_ashrrev_i32_e32 v17, 31, v16
	v_lshlrev_b64 v[22:23], 9, v[20:21]
	v_mad_i64_i32 v[20:21], s[26:27], v20, s62, v[12:13]
	v_ashrrev_i32_e32 v5, 31, v4
	v_lshlrev_b64 v[14:15], 9, v[10:11]
	v_mad_i64_i32 v[10:11], s[26:27], v10, s62, v[12:13]
	v_lshlrev_b64 v[18:19], 9, v[16:17]
	v_mad_i64_i32 v[16:17], s[26:27], v16, s62, v[12:13]
	v_lshl_add_u64 v[20:21], v[20:21], 0, v[6:7]
	v_lshlrev_b64 v[24:25], 9, v[4:5]
	v_mad_i64_i32 v[4:5], s[26:27], v4, s62, v[12:13]
	v_lshl_add_u64 v[14:15], v[8:9], 0, v[14:15]
	v_lshl_add_u64 v[10:11], v[10:11], 0, v[6:7]
	v_lshl_add_u64 v[18:19], v[8:9], 0, v[18:19]
	v_lshl_add_u64 v[16:17], v[16:17], 0, v[6:7]
	v_lshl_add_u64 v[22:23], v[8:9], 0, v[22:23]
	v_lshl_add_u64 v[20:21], v[20:21], 0, v[32:33]
	v_lshl_add_u64 v[4:5], v[4:5], 0, v[6:7]
	v_lshl_add_u64 v[10:11], v[10:11], 0, v[32:33]
	v_lshl_add_u64 v[16:17], v[16:17], 0, v[32:33]
	v_lshl_add_u64 v[8:9], v[8:9], 0, v[24:25]
	v_lshl_add_u64 v[4:5], v[4:5], 0, v[32:33]
	global_load_dword v45, v[14:15], off
	global_load_dword v33, v[10:11], off offset:512
	global_load_dword v47, v[18:19], off
	global_load_dword v69, v[16:17], off offset:512
	s_nop 0
	global_load_dword v49, v[22:23], off
	s_nop 0
	global_load_dword v70, v[20:21], off offset:512
	s_nop 0
	global_load_dword v51, v[8:9], off
	global_load_dword v71, v[4:5], off offset:512
	v_or_b32_e32 v18, v36, v59
	v_mad_i64_i32 v[4:5], s[26:27], v18, s62, v[12:13]
	v_or_b32_e32 v6, 1, v18
	v_or_b32_e32 v16, v36, v63
	v_or_b32_e32 v18, 33, v18
	v_lshlrev_b32_e32 v14, 8, v35
	v_mov_b32_e32 v15, v2
	v_mad_i64_i32 v[6:7], s[26:27], v6, s62, v[12:13]
	v_mad_i64_i32 v[16:17], s[26:27], v16, s62, v[12:13]
	v_mad_i64_i32 v[12:13], s[26:27], v18, s62, v[12:13]
	v_lshl_add_u64 v[4:5], v[4:5], 0, v[14:15]
	v_mov_b32_e32 v35, v2
	v_lshl_add_u64 v[6:7], v[6:7], 0, v[14:15]
	v_lshl_add_u64 v[16:17], v[16:17], 0, v[14:15]
	v_lshl_add_u64 v[12:13], v[12:13], 0, v[14:15]
	v_lshl_add_u64 v[4:5], v[4:5], 0, v[34:35]
	v_lshl_add_u64 v[8:9], v[6:7], 0, v[34:35]
	v_lshl_add_u64 v[16:17], v[16:17], 0, v[34:35]
	v_lshl_add_u64 v[18:19], v[12:13], 0, v[34:35]
	global_load_dwordx4 v[4:7], v[4:5], off offset:1024
	s_nop 0
	global_load_dwordx4 v[8:11], v[8:9], off offset:1024
	s_nop 0
	global_load_dwordx4 v[12:15], v[16:17], off offset:1024
	s_nop 0
	global_load_dwordx4 v[16:19], v[18:19], off offset:1024
	ds_read_b128 v[24:27], v67 offset:1024
	ds_read_b128 v[20:23], v67 offset:1088
	ds_read_b128 v[72:75], v68 offset:10240
	ds_read_b128 v[76:79], v68 offset:10304
	v_lshlrev_b64 v[52:53], 14, v[52:53]
	v_lshl_add_u64 v[52:53], v[30:31], 0, v[52:53]
	s_waitcnt lgkmcnt(1)
	v_mfma_f32_16x16x32_bf16 v[72:75], v[24:27], v[72:75], 0
	s_movk_i32 s25, 0x1000
	v_add_co_u32_e32 v80, vcc, s25, v52
	s_waitcnt lgkmcnt(0)
	v_mfma_f32_16x16x32_bf16 v[72:75], v[20:23], v[76:79], v[72:75]
	v_addc_co_u32_e32 v81, vcc, 0, v53, vcc
	s_movk_i32 s25, 0x2000
	ds_read_b128 v[76:79], v68 offset:12608
	v_add_co_u32_e32 v82, vcc, s25, v52
	s_nop 3
	v_cvt_pk_bf16_f32 v72, v72, v73
	v_cvt_pk_bf16_f32 v73, v74, v75
	global_store_dwordx2 v[52:53], v[72:73], off
	ds_read_b128 v[72:75], v68 offset:12544
	s_waitcnt lgkmcnt(0)
	v_mfma_f32_16x16x32_bf16 v[72:75], v[24:27], v[72:75], 0
	v_addc_co_u32_e32 v83, vcc, 0, v53, vcc
	s_movk_i32 s25, 0x3000
	v_mfma_f32_16x16x32_bf16 v[72:75], v[20:23], v[76:79], v[72:75]
	ds_read_b128 v[76:79], v68 offset:14912
	s_nop 6
	v_cvt_pk_bf16_f32 v72, v72, v73
	v_cvt_pk_bf16_f32 v73, v74, v75
	global_store_dwordx2 v[52:53], v[72:73], off offset:2048
	ds_read_b128 v[72:75], v68 offset:14848
	s_waitcnt lgkmcnt(0)
	v_mfma_f32_16x16x32_bf16 v[72:75], v[24:27], v[72:75], 0
	v_add_co_u32_e32 v52, vcc, s25, v52
	v_readlane_b32 s25, v254, 40
	v_mfma_f32_16x16x32_bf16 v[72:75], v[20:23], v[76:79], v[72:75]
	ds_read_b128 v[76:79], v68 offset:17216
	v_addc_co_u32_e32 v53, vcc, 0, v53, vcc
	v_add_u32_e32 v64, s25, v64
	v_readlane_b32 s25, v254, 42
	s_nop 3
	v_cvt_pk_bf16_f32 v72, v72, v73
	v_cvt_pk_bf16_f32 v73, v74, v75
	global_store_dwordx2 v[82:83], v[72:73], off offset:-4096
	ds_read_b128 v[72:75], v68 offset:17152
	s_waitcnt lgkmcnt(0)
	v_mfma_f32_16x16x32_bf16 v[72:75], v[24:27], v[72:75], 0
	v_add_u32_e32 v65, s25, v65
	v_readlane_b32 s25, v254, 44
	s_andn2_b64 vcc, exec, s[22:23]
	v_mfma_f32_16x16x32_bf16 v[72:75], v[20:23], v[76:79], v[72:75]
	ds_read_b128 v[76:79], v68 offset:19520
	v_add_u32_e32 v3, s25, v3
	s_nop 5
	v_cvt_pk_bf16_f32 v72, v72, v73
	v_cvt_pk_bf16_f32 v73, v74, v75
	global_store_dwordx2 v[80:81], v[72:73], off offset:2048
	ds_read_b128 v[72:75], v68 offset:19456
	s_waitcnt lgkmcnt(0)
	v_mfma_f32_16x16x32_bf16 v[72:75], v[24:27], v[72:75], 0
	v_mfma_f32_16x16x32_bf16 v[72:75], v[20:23], v[76:79], v[72:75]
	ds_read_b128 v[76:79], v68 offset:21824
	s_nop 6
	v_cvt_pk_bf16_f32 v72, v72, v73
	v_cvt_pk_bf16_f32 v73, v74, v75
	global_store_dwordx2 v[82:83], v[72:73], off
	ds_read_b128 v[72:75], v68 offset:21760
	s_waitcnt lgkmcnt(0)
	v_mfma_f32_16x16x32_bf16 v[72:75], v[24:27], v[72:75], 0
	v_mfma_f32_16x16x32_bf16 v[72:75], v[20:23], v[76:79], v[72:75]
	ds_read_b128 v[76:79], v68 offset:24128
	s_nop 6
	v_cvt_pk_bf16_f32 v72, v72, v73
	v_cvt_pk_bf16_f32 v73, v74, v75
	global_store_dwordx2 v[82:83], v[72:73], off offset:2048
	ds_read_b128 v[72:75], v68 offset:24064
	s_waitcnt lgkmcnt(0)
	v_mfma_f32_16x16x32_bf16 v[72:75], v[24:27], v[72:75], 0
	v_mfma_f32_16x16x32_bf16 v[72:75], v[20:23], v[76:79], v[72:75]
	s_nop 7
	v_cvt_pk_bf16_f32 v72, v72, v73
	v_cvt_pk_bf16_f32 v73, v74, v75
	global_store_dwordx2 v[52:53], v[72:73], off
	ds_read_b128 v[72:75], v68 offset:26368
	s_waitcnt lgkmcnt(0)
	v_mfma_f32_16x16x32_bf16 v[24:27], v[24:27], v[72:75], 0
	ds_read_b128 v[72:75], v68 offset:26432
	s_waitcnt lgkmcnt(0)
	v_mfma_f32_16x16x32_bf16 v[20:23], v[20:23], v[72:75], v[24:27]
	s_nop 7
	v_cvt_pk_bf16_f32 v20, v20, v21
	v_cvt_pk_bf16_f32 v21, v22, v23
	global_store_dwordx2 v[52:53], v[20:21], off offset:2048
	s_waitcnt vmcnt(27)
	v_lshlrev_b32_e32 v36, 16, v37
	v_and_b32_e32 v37, 0xffff0000, v37
	s_waitcnt vmcnt(25)
	v_lshlrev_b32_e32 v38, 16, v39
	v_and_b32_e32 v39, 0xffff0000, v39
	s_waitcnt vmcnt(23)
	v_lshlrev_b32_e32 v40, 16, v41
	v_and_b32_e32 v41, 0xffff0000, v41
	s_waitcnt vmcnt(21)
	v_lshlrev_b32_e32 v42, 16, v43
	v_and_b32_e32 v43, 0xffff0000, v43
	s_waitcnt vmcnt(19)
	v_lshlrev_b32_e32 v44, 16, v45
	v_and_b32_e32 v45, 0xffff0000, v45
	s_waitcnt vmcnt(17)
	v_lshlrev_b32_e32 v46, 16, v47
	v_and_b32_e32 v47, 0xffff0000, v47
	s_waitcnt vmcnt(15)
	v_lshlrev_b32_e32 v48, 16, v49
	v_and_b32_e32 v49, 0xffff0000, v49
	s_waitcnt vmcnt(13)
	v_lshlrev_b32_e32 v50, 16, v51
	v_and_b32_e32 v51, 0xffff0000, v51
	s_barrier
	s_cbranch_vccz .Lswap_ga_exit
	s_branch .LBB0_419
